# nt streaming policy on final RMSNorm phase x loads and d_out stores (once-read / once-written)
# speedup vs baseline: 1.0015x; 1.0015x over previous
; #define KP(f) ((decltype(Params::f))karg_ptr<(int)offsetof(Params, f)>())
; __device__ __forceinline__ float row_rstd(const float* ssq, int row) {
;     const f32x4* p = (const f32x4*)(ssq + (size_t)row * 16);
;     const f32x4 a = p[0], b = p[1], c = p[2], d = p[3];
;     const float s = ((a[0] + a[1]) + (a[2] + a[3])) + ((b[0] + b[1]) + (b[2] + b[3])) + ((c[0] + c[1]) + (c[2] + c[3])) + ((d[0] + d[1]) + (d[2] + d[3]));
;     return rsqrtf(s * (1.0f / 1024.0f) + 1e-6f);
; __device__ void phase_final() {
;     float* out = KP(out); const float* ssq = KP(ssq); const float* fg = KP(final_g);
;     const int lane = threadIdx.x & 63, gw = blockIdx.x * 8 + (threadIdx.x >> 6), nw = gridDim.x * 8;
;     for (int row = gw; row < T_ALL; row += nw) {
;         const float rs = row_rstd(ssq, row);
;         float* xr = out + (size_t)row * DM;
; #pragma unroll
;         for (int i = 0; i < 4; ++i) { const int c = i * 256 + lane * 4; const f32x4 v = *(const f32x4*)(xr + c); const f32x4 g = *(const f32x4*)(fg + c);
;             *(f32x4*)(xr + c) = v * rs * g; }
;     }
.LBB0_2319:
	s_or_b64 exec, exec, s[6:7]
	s_waitcnt lgkmcnt(0)
	s_barrier
	v_readlane_b32 s8, v230, 4
	s_load_dwordx2 s[2:3], s[0:1], 0xd8
	s_waitcnt lgkmcnt(0)
	s_load_dwordx2 s[4:5], s[0:1], 0x128
	s_waitcnt lgkmcnt(0)
	s_load_dwordx2 s[0:1], s[0:1], 0xd0
	s_waitcnt lgkmcnt(0)
	v_readlane_b32 s9, v230, 5
	s_and_saveexec_b64 s[6:7], s[8:9]
	s_cbranch_execz .LBB0_2322
	v_lshlrev_b32_e32 v0, 4, v166
	v_lshlrev_b64 v[2:3], 6, v[144:145]
	v_lshlrev_b64 v[4:5], 12, v[144:145]
	v_and_b32_e32 v0, 0x3f0, v0
	v_mov_b32_e32 v1, 0
	v_lshl_add_u64 v[2:3], s[4:5], 0, v[2:3]
	s_ashr_i32 s51, s50, 31
	v_lshl_or_b32 v4, v167, 4, v4
	v_lshl_add_u64 v[0:1], s[0:1], 0, v[0:1]
	v_lshl_add_u64 v[2:3], v[2:3], 0, 32
	s_lshl_b64 s[0:1], s[50:51], 6
	v_lshl_add_u64 v[4:5], s[2:3], 0, v[4:5]
	s_lshl_b64 s[2:3], s[50:51], 12
	s_mov_b64 s[4:5], 0
	v_mov_b32_e32 v6, 0x358637bd
	s_mov_b32 s6, 0x800000
	s_movk_i32 s7, 0x43ff
	global_load_dwordx4 v[40:43], v[0:1], off
	global_load_dwordx4 v[44:47], v[0:1], off offset:1024
	global_load_dwordx4 v[48:51], v[0:1], off offset:2048
	global_load_dwordx4 v[52:55], v[0:1], off offset:3072
	v_mov_b64_e32 v[92:93], v[4:5]
	global_load_dwordx4 v[8:11], v[2:3], off offset:-32
	global_load_dwordx4 v[12:15], v[2:3], off offset:-16
	global_load_dwordx4 v[16:19], v[2:3], off
	global_load_dwordx4 v[20:23], v[2:3], off offset:16
	global_load_dwordx4 v[24:27], v[4:5], off nt
	global_load_dwordx4 v[28:31], v[4:5], off offset:1024 nt
	global_load_dwordx4 v[32:35], v[4:5], off offset:2048 nt
	global_load_dwordx4 v[36:39], v[4:5], off offset:3072 nt
	v_add_u32_e32 v144, s50, v144
	v_lshl_add_u64 v[2:3], v[2:3], 0, s[0:1]
	v_lshl_add_u64 v[4:5], v[4:5], 0, s[2:3]
	v_cmp_ge_i32_e32 vcc, s7, v144
	s_cbranch_vccz .Lfin_lastA
	v_mov_b64_e32 v[94:95], v[4:5]
	global_load_dwordx4 v[56:59], v[2:3], off offset:-32
	global_load_dwordx4 v[60:63], v[2:3], off offset:-16
	global_load_dwordx4 v[64:67], v[2:3], off
	global_load_dwordx4 v[68:71], v[2:3], off offset:16
	global_load_dwordx4 v[72:75], v[4:5], off nt
	global_load_dwordx4 v[76:79], v[4:5], off offset:1024 nt
	global_load_dwordx4 v[80:83], v[4:5], off offset:2048 nt
	global_load_dwordx4 v[84:87], v[4:5], off offset:3072 nt
	s_waitcnt vmcnt(8)
	v_add_f32_e32 v96, v8, v9
	v_add_f32_e32 v97, v10, v11
	v_add_f32_e32 v98, v12, v13
	v_add_f32_e32 v99, v14, v15
	v_add_f32_e32 v100, v16, v17
	v_add_f32_e32 v101, v18, v19
	v_add_f32_e32 v102, v20, v21
	v_add_f32_e32 v103, v22, v23
	v_add_f32_e32 v96, v96, v97
	v_add_f32_e32 v98, v98, v99
	v_add_f32_e32 v100, v100, v101
	v_add_f32_e32 v102, v102, v103
	v_add_f32_e32 v96, v96, v98
	v_add_f32_e32 v96, v96, v100
	v_add_f32_e32 v96, v96, v102
	v_fmamk_f32 v96, v96, 0x3a800000, v6
	v_mul_f32_e32 v97, 0x4b800000, v96
	v_cmp_gt_f32_e32 vcc, s6, v96
	s_nop 1
	v_cndmask_b32_e32 v96, v96, v97, vcc
	v_rsq_f32_e32 v96, v96
	s_nop 0
	v_mul_f32_e32 v97, 0x45800000, v96
	v_cndmask_b32_e32 v90, v96, v97, vcc
	v_pk_mul_f32 v[24:25], v[24:25], v[90:91] op_sel_hi:[1,0]
	v_pk_mul_f32 v[26:27], v[26:27], v[90:91] op_sel_hi:[1,0]
	v_pk_mul_f32 v[24:25], v[40:41], v[24:25]
	v_pk_mul_f32 v[26:27], v[42:43], v[26:27]
	global_store_dwordx4 v[92:93], v[24:27], off nt
	v_pk_mul_f32 v[28:29], v[28:29], v[90:91] op_sel_hi:[1,0]
	v_pk_mul_f32 v[30:31], v[30:31], v[90:91] op_sel_hi:[1,0]
	v_pk_mul_f32 v[28:29], v[44:45], v[28:29]
	v_pk_mul_f32 v[30:31], v[46:47], v[30:31]
	global_store_dwordx4 v[92:93], v[28:31], off offset:1024 nt
	v_pk_mul_f32 v[32:33], v[32:33], v[90:91] op_sel_hi:[1,0]
	v_pk_mul_f32 v[34:35], v[34:35], v[90:91] op_sel_hi:[1,0]
	v_pk_mul_f32 v[32:33], v[48:49], v[32:33]
	v_pk_mul_f32 v[34:35], v[50:51], v[34:35]
	global_store_dwordx4 v[92:93], v[32:35], off offset:2048 nt
	v_pk_mul_f32 v[36:37], v[36:37], v[90:91] op_sel_hi:[1,0]
	v_pk_mul_f32 v[38:39], v[38:39], v[90:91] op_sel_hi:[1,0]
	v_pk_mul_f32 v[36:37], v[52:53], v[36:37]
	v_pk_mul_f32 v[38:39], v[54:55], v[38:39]
	global_store_dwordx4 v[92:93], v[36:39], off offset:3072 nt
.Lfin_loop:
	v_add_u32_e32 v144, s50, v144
	v_lshl_add_u64 v[2:3], v[2:3], 0, s[0:1]
	v_lshl_add_u64 v[4:5], v[4:5], 0, s[2:3]
	v_cmp_ge_i32_e32 vcc, s7, v144
	s_cbranch_vccz .Lfin_lastB
	v_mov_b64_e32 v[92:93], v[4:5]
	global_load_dwordx4 v[8:11], v[2:3], off offset:-32
	global_load_dwordx4 v[12:15], v[2:3], off offset:-16
	global_load_dwordx4 v[16:19], v[2:3], off
	global_load_dwordx4 v[20:23], v[2:3], off offset:16
	global_load_dwordx4 v[24:27], v[4:5], off nt
	global_load_dwordx4 v[28:31], v[4:5], off offset:1024 nt
	global_load_dwordx4 v[32:35], v[4:5], off offset:2048 nt
	global_load_dwordx4 v[36:39], v[4:5], off offset:3072 nt
	s_waitcnt vmcnt(12)
	v_add_f32_e32 v96, v56, v57
	v_add_f32_e32 v97, v58, v59
	v_add_f32_e32 v98, v60, v61
	v_add_f32_e32 v99, v62, v63
	v_add_f32_e32 v100, v64, v65
	v_add_f32_e32 v101, v66, v67
	v_add_f32_e32 v102, v68, v69
	v_add_f32_e32 v103, v70, v71
	v_add_f32_e32 v96, v96, v97
	v_add_f32_e32 v98, v98, v99
	v_add_f32_e32 v100, v100, v101
	v_add_f32_e32 v102, v102, v103
	v_add_f32_e32 v96, v96, v98
	v_add_f32_e32 v96, v96, v100
	v_add_f32_e32 v96, v96, v102
	v_fmamk_f32 v96, v96, 0x3a800000, v6
	v_mul_f32_e32 v97, 0x4b800000, v96
	v_cmp_gt_f32_e32 vcc, s6, v96
	s_nop 1
	v_cndmask_b32_e32 v96, v96, v97, vcc
	v_rsq_f32_e32 v96, v96
	s_nop 0
	v_mul_f32_e32 v97, 0x45800000, v96
	v_cndmask_b32_e32 v90, v96, v97, vcc
	v_pk_mul_f32 v[72:73], v[72:73], v[90:91] op_sel_hi:[1,0]
	v_pk_mul_f32 v[74:75], v[74:75], v[90:91] op_sel_hi:[1,0]
	v_pk_mul_f32 v[72:73], v[40:41], v[72:73]
	v_pk_mul_f32 v[74:75], v[42:43], v[74:75]
	global_store_dwordx4 v[94:95], v[72:75], off nt
	v_pk_mul_f32 v[76:77], v[76:77], v[90:91] op_sel_hi:[1,0]
	v_pk_mul_f32 v[78:79], v[78:79], v[90:91] op_sel_hi:[1,0]
	v_pk_mul_f32 v[76:77], v[44:45], v[76:77]
	v_pk_mul_f32 v[78:79], v[46:47], v[78:79]
	global_store_dwordx4 v[94:95], v[76:79], off offset:1024 nt
	v_pk_mul_f32 v[80:81], v[80:81], v[90:91] op_sel_hi:[1,0]
	v_pk_mul_f32 v[82:83], v[82:83], v[90:91] op_sel_hi:[1,0]
	v_pk_mul_f32 v[80:81], v[48:49], v[80:81]
	v_pk_mul_f32 v[82:83], v[50:51], v[82:83]
	global_store_dwordx4 v[94:95], v[80:83], off offset:2048 nt
	v_pk_mul_f32 v[84:85], v[84:85], v[90:91] op_sel_hi:[1,0]
	v_pk_mul_f32 v[86:87], v[86:87], v[90:91] op_sel_hi:[1,0]
	v_pk_mul_f32 v[84:85], v[52:53], v[84:85]
	v_pk_mul_f32 v[86:87], v[54:55], v[86:87]
	global_store_dwordx4 v[94:95], v[84:87], off offset:3072 nt
	v_add_u32_e32 v144, s50, v144
	v_lshl_add_u64 v[2:3], v[2:3], 0, s[0:1]
	v_lshl_add_u64 v[4:5], v[4:5], 0, s[2:3]
	v_cmp_ge_i32_e32 vcc, s7, v144
	s_cbranch_vccz .Lfin_lastA
; #define KP(f) ((decltype(Params::f))karg_ptr<(int)offsetof(Params, f)>())
; __device__ __forceinline__ float row_rstd(const float* ssq, int row) {
;     const f32x4* p = (const f32x4*)(ssq + (size_t)row * 16);
;     const f32x4 a = p[0], b = p[1], c = p[2], d = p[3];
;     const float s = ((a[0] + a[1]) + (a[2] + a[3])) + ((b[0] + b[1]) + (b[2] + b[3])) + ((c[0] + c[1]) + (c[2] + c[3])) + ((d[0] + d[1]) + (d[2] + d[3]));
;     return rsqrtf(s * (1.0f / 1024.0f) + 1e-6f);
; __device__ void phase_final() {
;     float* out = KP(out); const float* ssq = KP(ssq); const float* fg = KP(final_g);
;     const int lane = threadIdx.x & 63, gw = blockIdx.x * 8 + (threadIdx.x >> 6), nw = gridDim.x * 8;
;     for (int row = gw; row < T_ALL; row += nw) {
;         const float rs = row_rstd(ssq, row);
;         float* xr = out + (size_t)row * DM;
; #pragma unroll
;         for (int i = 0; i < 4; ++i) { const int c = i * 256 + lane * 4; const f32x4 v = *(const f32x4*)(xr + c); const f32x4 g = *(const f32x4*)(fg + c);
;             *(f32x4*)(xr + c) = v * rs * g; }
;     }
	v_mov_b64_e32 v[94:95], v[4:5]
	global_load_dwordx4 v[56:59], v[2:3], off offset:-32
	global_load_dwordx4 v[60:63], v[2:3], off offset:-16
	global_load_dwordx4 v[64:67], v[2:3], off
	global_load_dwordx4 v[68:71], v[2:3], off offset:16
	global_load_dwordx4 v[72:75], v[4:5], off nt
	global_load_dwordx4 v[76:79], v[4:5], off offset:1024 nt
	global_load_dwordx4 v[80:83], v[4:5], off offset:2048 nt
	global_load_dwordx4 v[84:87], v[4:5], off offset:3072 nt
	s_waitcnt vmcnt(12)
	v_add_f32_e32 v96, v8, v9
	v_add_f32_e32 v97, v10, v11
	v_add_f32_e32 v98, v12, v13
	v_add_f32_e32 v99, v14, v15
	v_add_f32_e32 v100, v16, v17
	v_add_f32_e32 v101, v18, v19
	v_add_f32_e32 v102, v20, v21
	v_add_f32_e32 v103, v22, v23
	v_add_f32_e32 v96, v96, v97
	v_add_f32_e32 v98, v98, v99
	v_add_f32_e32 v100, v100, v101
	v_add_f32_e32 v102, v102, v103
	v_add_f32_e32 v96, v96, v98
	v_add_f32_e32 v96, v96, v100
	v_add_f32_e32 v96, v96, v102
	v_fmamk_f32 v96, v96, 0x3a800000, v6
	v_mul_f32_e32 v97, 0x4b800000, v96
	v_cmp_gt_f32_e32 vcc, s6, v96
	s_nop 1
	v_cndmask_b32_e32 v96, v96, v97, vcc
	v_rsq_f32_e32 v96, v96
	s_nop 0
	v_mul_f32_e32 v97, 0x45800000, v96
	v_cndmask_b32_e32 v90, v96, v97, vcc
	v_pk_mul_f32 v[24:25], v[24:25], v[90:91] op_sel_hi:[1,0]
	v_pk_mul_f32 v[26:27], v[26:27], v[90:91] op_sel_hi:[1,0]
	v_pk_mul_f32 v[24:25], v[40:41], v[24:25]
	v_pk_mul_f32 v[26:27], v[42:43], v[26:27]
	global_store_dwordx4 v[92:93], v[24:27], off nt
	v_pk_mul_f32 v[28:29], v[28:29], v[90:91] op_sel_hi:[1,0]
	v_pk_mul_f32 v[30:31], v[30:31], v[90:91] op_sel_hi:[1,0]
	v_pk_mul_f32 v[28:29], v[44:45], v[28:29]
	v_pk_mul_f32 v[30:31], v[46:47], v[30:31]
	global_store_dwordx4 v[92:93], v[28:31], off offset:1024 nt
	v_pk_mul_f32 v[32:33], v[32:33], v[90:91] op_sel_hi:[1,0]
	v_pk_mul_f32 v[34:35], v[34:35], v[90:91] op_sel_hi:[1,0]
	v_pk_mul_f32 v[32:33], v[48:49], v[32:33]
	v_pk_mul_f32 v[34:35], v[50:51], v[34:35]
	global_store_dwordx4 v[92:93], v[32:35], off offset:2048 nt
	v_pk_mul_f32 v[36:37], v[36:37], v[90:91] op_sel_hi:[1,0]
	v_pk_mul_f32 v[38:39], v[38:39], v[90:91] op_sel_hi:[1,0]
	v_pk_mul_f32 v[36:37], v[52:53], v[36:37]
	v_pk_mul_f32 v[38:39], v[54:55], v[38:39]
	global_store_dwordx4 v[92:93], v[36:39], off offset:3072 nt
	s_branch .Lfin_loop
.Lfin_lastA:
	s_waitcnt vmcnt(0)
	v_add_f32_e32 v96, v8, v9
	v_add_f32_e32 v97, v10, v11
	v_add_f32_e32 v98, v12, v13
	v_add_f32_e32 v99, v14, v15
	v_add_f32_e32 v100, v16, v17
	v_add_f32_e32 v101, v18, v19
	v_add_f32_e32 v102, v20, v21
	v_add_f32_e32 v103, v22, v23
	v_add_f32_e32 v96, v96, v97
	v_add_f32_e32 v98, v98, v99
	v_add_f32_e32 v100, v100, v101
	v_add_f32_e32 v102, v102, v103
	v_add_f32_e32 v96, v96, v98
	v_add_f32_e32 v96, v96, v100
	v_add_f32_e32 v96, v96, v102
	v_fmamk_f32 v96, v96, 0x3a800000, v6
	v_mul_f32_e32 v97, 0x4b800000, v96
	v_cmp_gt_f32_e32 vcc, s6, v96
	s_nop 1
	v_cndmask_b32_e32 v96, v96, v97, vcc
	v_rsq_f32_e32 v96, v96
	s_nop 0
	v_mul_f32_e32 v97, 0x45800000, v96
	v_cndmask_b32_e32 v90, v96, v97, vcc
	v_pk_mul_f32 v[24:25], v[24:25], v[90:91] op_sel_hi:[1,0]
	v_pk_mul_f32 v[26:27], v[26:27], v[90:91] op_sel_hi:[1,0]
	v_pk_mul_f32 v[24:25], v[40:41], v[24:25]
	v_pk_mul_f32 v[26:27], v[42:43], v[26:27]
	global_store_dwordx4 v[92:93], v[24:27], off nt
	v_pk_mul_f32 v[28:29], v[28:29], v[90:91] op_sel_hi:[1,0]
	v_pk_mul_f32 v[30:31], v[30:31], v[90:91] op_sel_hi:[1,0]
	v_pk_mul_f32 v[28:29], v[44:45], v[28:29]
	v_pk_mul_f32 v[30:31], v[46:47], v[30:31]
	global_store_dwordx4 v[92:93], v[28:31], off offset:1024 nt
	v_pk_mul_f32 v[32:33], v[32:33], v[90:91] op_sel_hi:[1,0]
	v_pk_mul_f32 v[34:35], v[34:35], v[90:91] op_sel_hi:[1,0]
	v_pk_mul_f32 v[32:33], v[48:49], v[32:33]
	v_pk_mul_f32 v[34:35], v[50:51], v[34:35]
	global_store_dwordx4 v[92:93], v[32:35], off offset:2048 nt
	v_pk_mul_f32 v[36:37], v[36:37], v[90:91] op_sel_hi:[1,0]
	v_pk_mul_f32 v[38:39], v[38:39], v[90:91] op_sel_hi:[1,0]
	v_pk_mul_f32 v[36:37], v[52:53], v[36:37]
	v_pk_mul_f32 v[38:39], v[54:55], v[38:39]
	global_store_dwordx4 v[92:93], v[36:39], off offset:3072 nt
	s_branch .LBB0_2322
.Lfin_lastB:
	s_waitcnt vmcnt(0)
	v_add_f32_e32 v96, v56, v57
	v_add_f32_e32 v97, v58, v59
	v_add_f32_e32 v98, v60, v61
	v_add_f32_e32 v99, v62, v63
	v_add_f32_e32 v100, v64, v65
	v_add_f32_e32 v101, v66, v67
	v_add_f32_e32 v102, v68, v69
	v_add_f32_e32 v103, v70, v71
	v_add_f32_e32 v96, v96, v97
	v_add_f32_e32 v98, v98, v99
	v_add_f32_e32 v100, v100, v101
	v_add_f32_e32 v102, v102, v103
	v_add_f32_e32 v96, v96, v98
	v_add_f32_e32 v96, v96, v100
	v_add_f32_e32 v96, v96, v102
	v_fmamk_f32 v96, v96, 0x3a800000, v6
	v_mul_f32_e32 v97, 0x4b800000, v96
	v_cmp_gt_f32_e32 vcc, s6, v96
	s_nop 1
	v_cndmask_b32_e32 v96, v96, v97, vcc
	v_rsq_f32_e32 v96, v96
	s_nop 0
	v_mul_f32_e32 v97, 0x45800000, v96
	v_cndmask_b32_e32 v90, v96, v97, vcc
	v_pk_mul_f32 v[72:73], v[72:73], v[90:91] op_sel_hi:[1,0]
	v_pk_mul_f32 v[74:75], v[74:75], v[90:91] op_sel_hi:[1,0]
	v_pk_mul_f32 v[72:73], v[40:41], v[72:73]
	v_pk_mul_f32 v[74:75], v[42:43], v[74:75]
	global_store_dwordx4 v[94:95], v[72:75], off nt
	v_pk_mul_f32 v[76:77], v[76:77], v[90:91] op_sel_hi:[1,0]
	v_pk_mul_f32 v[78:79], v[78:79], v[90:91] op_sel_hi:[1,0]
	v_pk_mul_f32 v[76:77], v[44:45], v[76:77]
	v_pk_mul_f32 v[78:79], v[46:47], v[78:79]
	global_store_dwordx4 v[94:95], v[76:79], off offset:1024 nt
	v_pk_mul_f32 v[80:81], v[80:81], v[90:91] op_sel_hi:[1,0]
	v_pk_mul_f32 v[82:83], v[82:83], v[90:91] op_sel_hi:[1,0]
	v_pk_mul_f32 v[80:81], v[48:49], v[80:81]
	v_pk_mul_f32 v[82:83], v[50:51], v[82:83]
	global_store_dwordx4 v[94:95], v[80:83], off offset:2048 nt
	v_pk_mul_f32 v[84:85], v[84:85], v[90:91] op_sel_hi:[1,0]
	v_pk_mul_f32 v[86:87], v[86:87], v[90:91] op_sel_hi:[1,0]
	v_pk_mul_f32 v[84:85], v[52:53], v[84:85]
	v_pk_mul_f32 v[86:87], v[54:55], v[86:87]
	global_store_dwordx4 v[94:95], v[84:87], off offset:3072 nt
